# adds: sgu_unit gvT LDS image XOR-swizzled by row>>3 (16-way ds_write_b16 bank conflict to 2-way; reader applies same swizzle per ks)
# speedup vs baseline: 1.0016x; 1.0016x over previous
; #define LAS __attribute__((address_space(3)))
; __device__ __forceinline__ unsigned cvt_pk_bf16(float lo, float hi) { const f32x2 v = {lo, hi}; const bf16x2_t b = __builtin_convertvector(v, bf16x2_t); return __builtin_bit_cast(unsigned, b); }
; __device__ __forceinline__ float bf_lo(unsigned u) { return __uint_as_float(u << 16); }
; __device__ __forceinline__ float bf_hi(unsigned u) { return __uint_as_float(u & 0xffff0000u); }
; template <bool STORE> __device__ __forceinline__ void sgu_unit(LAS unsigned char* lds, const bf16_t* GEL, const float* STAT, bf16_t* GU, const float* sw, const float* sb, const float* lng, const float* lnb, int unit, const int wave_s) {
;     ...
;     for (int i = 0; i < 8; ++i) { const int id = tid + 512 * i, t = id >> 5, s4 = (id & 31) * 4; const f32x4 v = *(const f32x4*)(sw + (size_t)g * 16384 + t * 128 + s4);
;         u32x2 w; w.x = cvt_pk_bf16(v[0], v[1]); w.y = cvt_pk_bf16(v[2], v[3]); *(LAS u32x2*)(lds + SG_WL + t * 272 + s4 * 2) = w; }
;     __syncthreads();
; #pragma unroll
;     for (int i = 0; i < 4; ++i) { const int id = tid + 512 * i, s = id >> 4, cc = (id & 15) * 8; const u32x4 v = gv4[i];
;         const float mean = st[2 * s], rstd = st[2 * s + 1];
;         const f32x4 g0 = *(const f32x4*)(lng + c0 + cc), g1 = *(const f32x4*)(lng + c0 + cc + 4), b0 = *(const f32x4*)(lnb + c0 + cc), b1 = *(const f32x4*)(lnb + c0 + cc + 4);
;         float x[8] = {bf_lo(v.x), bf_hi(v.x), bf_lo(v.y), bf_hi(v.y), bf_lo(v.z), bf_hi(v.z), bf_lo(v.w), bf_hi(v.w)};
; #pragma unroll
;         for (int k = 0; k < 8; ++k) { const float gg = k < 4 ? g0[k & 3] : g1[k & 3], bb = k < 4 ? b0[k & 3] : b1[k & 3]; const float y = (x[k] - mean) * rstd * gg + bb;
;             *(LAS bf16_t*)(lds + SG_GL + (cc + k) * 272 + s * 2) = (bf16_t)(cvt_pk_bf16(y, 0.f) & 0xffffu); } }
.LBB0_849:
	s_or_b64 exec, exec, s[34:35]
	v_lshlrev_b32_e32 v0, 2, v34
	s_lshl_b32 s34, s45, 16
	v_and_b32_e32 v7, 0x7c, v0
	s_add_u32 s34, s16, s34
	s_addc_u32 s35, s18, 0
	v_lshlrev_b32_e32 v0, 2, v7
	v_lshl_add_u64 v[12:13], s[34:35], 0, v[0:1]
	v_lshl_add_u32 v0, v7, 1, 0
	v_ashrrev_i32_e32 v7, 5, v6
	v_lshlrev_b32_e32 v8, 7, v7
	v_ashrrev_i32_e32 v9, 31, v8
	v_lshl_add_u64 v[8:9], v[8:9], 2, v[12:13]
	global_load_dwordx4 v[196:199], v[8:9], off
	v_mov_b32_e32 v228, v7
	s_movk_i32 s45, 0x110
	v_ashrrev_i32_e32 v229, 5, v37
	v_lshlrev_b32_e32 v8, 7, v229
	v_ashrrev_i32_e32 v9, 31, v8
	v_lshl_add_u64 v[8:9], v[8:9], 2, v[12:13]
	global_load_dwordx4 v[200:203], v[8:9], off
	v_ashrrev_i32_e32 v230, 5, v36
	v_lshlrev_b32_e32 v8, 7, v230
	v_ashrrev_i32_e32 v9, 31, v8
	v_lshl_add_u64 v[8:9], v[8:9], 2, v[12:13]
	global_load_dwordx4 v[204:207], v[8:9], off
	v_ashrrev_i32_e32 v231, 5, v35
	v_lshlrev_b32_e32 v8, 7, v231
	v_ashrrev_i32_e32 v9, 31, v8
	v_lshl_add_u64 v[8:9], v[8:9], 2, v[12:13]
	global_load_dwordx4 v[208:211], v[8:9], off
	v_add_u32_e32 v232, 0x800, v6
	v_ashrrev_i32_e32 v232, 5, v232
	v_lshlrev_b32_e32 v8, 7, v232
	v_ashrrev_i32_e32 v9, 31, v8
	v_lshl_add_u64 v[8:9], v[8:9], 2, v[12:13]
	global_load_dwordx4 v[212:215], v[8:9], off
	v_add_u32_e32 v233, 0xa00, v6
	v_ashrrev_i32_e32 v233, 5, v233
	v_lshlrev_b32_e32 v8, 7, v233
	v_ashrrev_i32_e32 v9, 31, v8
	v_lshl_add_u64 v[8:9], v[8:9], 2, v[12:13]
	global_load_dwordx4 v[216:219], v[8:9], off
	v_add_u32_e32 v234, 0xc00, v6
	v_ashrrev_i32_e32 v234, 5, v234
	v_lshlrev_b32_e32 v8, 7, v234
	v_ashrrev_i32_e32 v9, 31, v8
	v_lshl_add_u64 v[8:9], v[8:9], 2, v[12:13]
	global_load_dwordx4 v[220:223], v[8:9], off
	v_add_u32_e32 v235, 0xe00, v6
	v_ashrrev_i32_e32 v235, 5, v235
	v_lshlrev_b32_e32 v8, 7, v235
	v_ashrrev_i32_e32 v9, 31, v8
	v_lshl_add_u64 v[8:9], v[8:9], 2, v[12:13]
	global_load_dwordx4 v[224:227], v[8:9], off
	s_waitcnt vmcnt(11)
	v_lshlrev_b32_e32 v42, 16, v31
	v_and_b32_e32 v31, 0xffff0000, v31
	v_lshlrev_b32_e32 v43, 16, v32
	v_and_b32_e32 v32, 0xffff0000, v32
	v_lshlrev_b32_e32 v44, 16, v33
	v_and_b32_e32 v33, 0xffff0000, v33
	v_bfe_u32 v46, v34, 5, 1
	v_ashrrev_i32_e32 v6, 3, v6
	v_and_b32_e32 v39, -2, v6
	v_lshl_or_b32 v6, v6, 2, 4
	s_waitcnt vmcnt(7)
	v_cvt_pk_bf16_f32 v8, v196, v197
	v_cvt_pk_bf16_f32 v9, v198, v199
	v_mad_u64_u32 v[10:11], s[34:35], v228, s45, v[0:1]
	ds_write_b64 v10, v[8:9]
	s_waitcnt vmcnt(6)
	v_cvt_pk_bf16_f32 v8, v200, v201
	v_cvt_pk_bf16_f32 v9, v202, v203
	v_mad_u64_u32 v[10:11], s[34:35], v229, s45, v[0:1]
	ds_write_b64 v10, v[8:9]
	s_waitcnt vmcnt(5)
	v_cvt_pk_bf16_f32 v8, v204, v205
	v_cvt_pk_bf16_f32 v9, v206, v207
	v_mad_u64_u32 v[10:11], s[34:35], v230, s45, v[0:1]
	ds_write_b64 v10, v[8:9]
	s_waitcnt vmcnt(4)
	v_cvt_pk_bf16_f32 v8, v208, v209
	v_cvt_pk_bf16_f32 v9, v210, v211
	v_mad_u64_u32 v[10:11], s[34:35], v231, s45, v[0:1]
	ds_write_b64 v10, v[8:9]
	s_waitcnt vmcnt(3)
	v_cvt_pk_bf16_f32 v8, v212, v213
	v_cvt_pk_bf16_f32 v9, v214, v215
	v_mad_u64_u32 v[10:11], s[34:35], v232, s45, v[0:1]
	ds_write_b64 v10, v[8:9]
	s_waitcnt vmcnt(2)
	v_cvt_pk_bf16_f32 v8, v216, v217
	v_cvt_pk_bf16_f32 v9, v218, v219
	v_mad_u64_u32 v[10:11], s[34:35], v233, s45, v[0:1]
	ds_write_b64 v10, v[8:9]
	s_waitcnt vmcnt(1)
	v_cvt_pk_bf16_f32 v8, v220, v221
	v_cvt_pk_bf16_f32 v9, v222, v223
	v_mad_u64_u32 v[10:11], s[34:35], v234, s45, v[0:1]
	ds_write_b64 v10, v[8:9]
	s_waitcnt vmcnt(0)
	v_cvt_pk_bf16_f32 v8, v224, v225
	v_cvt_pk_bf16_f32 v9, v226, v227
	v_mad_u64_u32 v[10:11], s[34:35], v235, s45, v[0:1]
	ds_write_b64 v10, v[8:9]
	s_lshl_b32 s34, s44, 2
	s_add_u32 s46, s19, s34
	s_addc_u32 s47, s20, 0
	s_add_u32 s48, s21, s34
	s_addc_u32 s49, s28, 0
	s_add_i32 s34, 0, 0x11000
	v_lshlrev_b32_e32 v0, 2, v38
	v_lshl_add_u32 v7, v39, 2, s34
	v_add_u32_e32 v6, s34, v6
	s_waitcnt lgkmcnt(0)
	s_barrier
	ds_read_b32 v40, v7
	ds_read_b32 v41, v6
	global_load_dwordx4 v[6:9], v0, s[46:47] offset:16
	global_load_dwordx4 v[14:17], v0, s[46:47]
	global_load_dwordx4 v[10:13], v0, s[48:49] offset:16
	global_load_dwordx4 v[22:25], v0, s[48:49]
	v_lshlrev_b32_e32 v0, 16, v30
	v_and_b32_e32 v30, 0xffff0000, v30
	s_waitcnt lgkmcnt(1)
	v_sub_f32_e32 v0, v0, v40
	s_waitcnt lgkmcnt(0)
	v_mul_f32_e32 v0, v41, v0
	v_sub_f32_e32 v30, v30, v40
	v_mul_f32_e32 v30, v41, v30
	s_waitcnt vmcnt(0)
	v_fma_f32 v0, v0, v14, v22
	v_cvt_pk_bf16_f32 v45, v0, s0
	v_lshlrev_b32_e32 v240, 1, v38
	v_mul_u32_u24_e32 v0, 0x110, v38
	v_fma_f32 v30, v30, v15, v23
	v_xor_b32_e32 v241, v240, v39
	v_add3_u32 v38, 0, v241, v0
	v_cvt_pk_bf16_f32 v30, v30, s0
	ds_write_b16 v38, v30 offset:35088
	v_sub_f32_e32 v30, v42, v40
	v_mul_f32_e32 v30, v41, v30
	v_fma_f32 v30, v30, v16, v24
	v_cvt_pk_bf16_f32 v30, v30, s0
	ds_write_b16 v38, v30 offset:35360
	v_sub_f32_e32 v30, v31, v40
	v_mul_f32_e32 v30, v41, v30
	v_fma_f32 v30, v30, v17, v25
	v_cvt_pk_bf16_f32 v30, v30, s0
	ds_write_b16 v38, v30 offset:35632
	v_sub_f32_e32 v30, v43, v40
	v_mul_f32_e32 v30, v41, v30
	v_fma_f32 v30, v30, v6, v10
	v_cvt_pk_bf16_f32 v30, v30, s0
	ds_write_b16 v38, v30 offset:35904
	v_sub_f32_e32 v30, v32, v40
	v_mul_f32_e32 v30, v41, v30
	v_fma_f32 v30, v30, v7, v11
	v_cvt_pk_bf16_f32 v30, v30, s0
	ds_write_b16 v38, v30 offset:36176
	v_sub_f32_e32 v30, v44, v40
	v_mul_f32_e32 v30, v41, v30
	v_fma_f32 v30, v30, v8, v12
	v_cvt_pk_bf16_f32 v30, v30, s0
	ds_write_b16 v38, v30 offset:36448
	v_sub_f32_e32 v30, v33, v40
	v_mul_f32_e32 v30, v41, v30
	v_fma_f32 v30, v30, v9, v13
	v_cvt_pk_bf16_f32 v30, v30, s0
	ds_write_b16 v38, v30 offset:36720
	v_ashrrev_i32_e32 v30, 3, v37
	v_and_b32_e32 v31, -2, v30
	v_lshl_add_u32 v32, v31, 2, s34
	v_lshl_or_b32 v30, v30, 2, 4
	ds_read_b32 v32, v32
	v_add_u32_e32 v30, s34, v30
	ds_read_b32 v30, v30
	v_lshlrev_b32_e32 v33, 16, v26
	v_and_b32_e32 v26, 0xffff0000, v26
	s_waitcnt lgkmcnt(1)
; #define LAS __attribute__((address_space(3)))
; __device__ __forceinline__ unsigned cvt_pk_bf16(float lo, float hi) { const f32x2 v = {lo, hi}; const bf16x2_t b = __builtin_convertvector(v, bf16x2_t); return __builtin_bit_cast(unsigned, b); }
; __device__ __forceinline__ float bf_lo(unsigned u) { return __uint_as_float(u << 16); }
; __device__ __forceinline__ float bf_hi(unsigned u) { return __uint_as_float(u & 0xffff0000u); }
; template <bool STORE> __device__ __forceinline__ void sgu_unit(LAS unsigned char* lds, const bf16_t* GEL, const float* STAT, bf16_t* GU, const float* sw, const float* sb, const float* lng, const float* lnb, int unit, const int wave_s) {
;     ...
;     for (int i = 0; i < 4; ++i) { const int id = tid + 512 * i, s = id >> 4, cc = (id & 15) * 8; const u32x4 v = gv4[i];
;         const float mean = st[2 * s], rstd = st[2 * s + 1];
;         const f32x4 g0 = *(const f32x4*)(lng + c0 + cc), g1 = *(const f32x4*)(lng + c0 + cc + 4), b0 = *(const f32x4*)(lnb + c0 + cc), b1 = *(const f32x4*)(lnb + c0 + cc + 4);
;         float x[8] = {bf_lo(v.x), bf_hi(v.x), bf_lo(v.y), bf_hi(v.y), bf_lo(v.z), bf_hi(v.z), bf_lo(v.w), bf_hi(v.w)};
; #pragma unroll
;         for (int k = 0; k < 8; ++k) { const float gg = k < 4 ? g0[k & 3] : g1[k & 3], bb = k < 4 ? b0[k & 3] : b1[k & 3]; const float y = (x[k] - mean) * rstd * gg + bb;
;             *(LAS bf16_t*)(lds + SG_GL + (cc + k) * 272 + s * 2) = (bf16_t)(cvt_pk_bf16(y, 0.f) & 0xffffu); } }
	v_sub_f32_e32 v26, v26, v32
	v_lshlrev_b32_e32 v37, 16, v27
	s_waitcnt lgkmcnt(0)
	v_mul_f32_e32 v26, v30, v26
	v_fma_f32 v26, v15, v26, v23
	v_xor_b32_e32 v241, v240, v31
	v_add3_u32 v31, 0, v241, v0
	v_cvt_pk_bf16_f32 v26, v26, s0
	ds_write_b16 v38, v45 offset:34816
	ds_write_b16 v31, v26 offset:35088
	v_sub_f32_e32 v26, v37, v32
	v_mul_f32_e32 v26, v30, v26
	v_fma_f32 v26, v16, v26, v24
	v_and_b32_e32 v27, 0xffff0000, v27
	v_cvt_pk_bf16_f32 v26, v26, s0
	ds_write_b16 v31, v26 offset:35360
	v_sub_f32_e32 v26, v27, v32
	v_mul_f32_e32 v26, v30, v26
	v_fma_f32 v26, v17, v26, v25
	v_lshlrev_b32_e32 v38, 16, v28
	v_cvt_pk_bf16_f32 v26, v26, s0
	ds_write_b16 v31, v26 offset:35632
	v_sub_f32_e32 v26, v38, v32
	v_mul_f32_e32 v26, v30, v26
	v_fma_f32 v26, v6, v26, v10
	v_and_b32_e32 v28, 0xffff0000, v28
	v_cvt_pk_bf16_f32 v26, v26, s0
	ds_write_b16 v31, v26 offset:35904
	v_sub_f32_e32 v26, v28, v32
	v_mul_f32_e32 v26, v30, v26
	v_fma_f32 v26, v7, v26, v11
	v_lshlrev_b32_e32 v39, 16, v29
	v_cvt_pk_bf16_f32 v26, v26, s0
	ds_write_b16 v31, v26 offset:36176
	v_sub_f32_e32 v26, v39, v32
	v_mul_f32_e32 v26, v30, v26
	v_fma_f32 v26, v8, v26, v12
	v_and_b32_e32 v29, 0xffff0000, v29
	v_cvt_pk_bf16_f32 v26, v26, s0
	ds_write_b16 v31, v26 offset:36448
	v_sub_f32_e32 v26, v29, v32
	v_mul_f32_e32 v26, v30, v26
	v_fma_f32 v26, v9, v26, v13
	v_cvt_pk_bf16_f32 v26, v26, s0
	ds_write_b16 v31, v26 offset:36720
	v_ashrrev_i32_e32 v26, 3, v36
	v_and_b32_e32 v27, -2, v26
	v_lshl_add_u32 v28, v27, 2, s34
	v_lshl_or_b32 v26, v26, 2, 4
	ds_read_b32 v28, v28
	v_add_u32_e32 v26, s34, v26
	ds_read_b32 v26, v26
	v_lshlrev_b32_e32 v29, 16, v18
	v_and_b32_e32 v18, 0xffff0000, v18
	v_sub_f32_e32 v33, v33, v32
	s_waitcnt lgkmcnt(1)
	v_sub_f32_e32 v18, v18, v28
	v_mul_f32_e32 v33, v30, v33
	s_waitcnt lgkmcnt(0)
	v_mul_f32_e32 v18, v26, v18
	v_fma_f32 v33, v14, v33, v22
	v_fma_f32 v18, v15, v18, v23
	v_cvt_pk_bf16_f32 v33, v33, s0
	v_lshlrev_b32_e32 v30, 16, v19
	v_xor_b32_e32 v241, v240, v27
	v_add3_u32 v27, 0, v241, v0
	v_cvt_pk_bf16_f32 v18, v18, s0
	ds_write_b16 v31, v33 offset:34816
	ds_write_b16 v27, v18 offset:35088
	v_sub_f32_e32 v18, v30, v28
	v_mul_f32_e32 v18, v26, v18
	v_fma_f32 v18, v16, v18, v24
	v_and_b32_e32 v19, 0xffff0000, v19
	v_cvt_pk_bf16_f32 v18, v18, s0
	ds_write_b16 v27, v18 offset:35360
	v_sub_f32_e32 v18, v19, v28
	v_mul_f32_e32 v18, v26, v18
	v_fma_f32 v18, v17, v18, v25
	v_lshlrev_b32_e32 v31, 16, v20
	v_cvt_pk_bf16_f32 v18, v18, s0
	ds_write_b16 v27, v18 offset:35632
	v_sub_f32_e32 v18, v31, v28
	v_mul_f32_e32 v18, v26, v18
	v_fma_f32 v18, v6, v18, v10
	v_and_b32_e32 v20, 0xffff0000, v20
	v_cvt_pk_bf16_f32 v18, v18, s0
	ds_write_b16 v27, v18 offset:35904
	v_sub_f32_e32 v18, v20, v28
	v_mul_f32_e32 v18, v26, v18
	v_fma_f32 v18, v7, v18, v11
	v_lshlrev_b32_e32 v32, 16, v21
	v_cvt_pk_bf16_f32 v18, v18, s0
	ds_write_b16 v27, v18 offset:36176
	v_sub_f32_e32 v18, v32, v28
	v_mul_f32_e32 v18, v26, v18
	v_fma_f32 v18, v8, v18, v12
	v_and_b32_e32 v21, 0xffff0000, v21
	v_cvt_pk_bf16_f32 v18, v18, s0
	ds_write_b16 v27, v18 offset:36448
	v_sub_f32_e32 v18, v21, v28
	v_mul_f32_e32 v18, v26, v18
	v_fma_f32 v18, v9, v18, v13
	v_ashrrev_i32_e32 v19, 3, v35
	v_cvt_pk_bf16_f32 v18, v18, s0
	v_and_b32_e32 v20, -2, v19
	ds_write_b16 v27, v18 offset:36720
	v_lshl_add_u32 v18, v20, 2, s34
	v_lshl_or_b32 v19, v19, 2, 4
	ds_read_b32 v18, v18
	v_add_u32_e32 v19, s34, v19
	ds_read_b32 v19, v19
	v_lshlrev_b32_e32 v21, 16, v2
	v_and_b32_e32 v2, 0xffff0000, v2
	v_sub_f32_e32 v29, v29, v28
	s_waitcnt lgkmcnt(1)
	v_sub_f32_e32 v2, v2, v18
	v_mul_f32_e32 v29, v26, v29
	s_waitcnt lgkmcnt(0)
	v_mul_f32_e32 v2, v19, v2
	v_fma_f32 v29, v14, v29, v22
	v_fma_f32 v2, v15, v2, v23
	v_cvt_pk_bf16_f32 v29, v29, s0
	v_lshlrev_b32_e32 v26, 16, v3
	v_xor_b32_e32 v241, v240, v20
	v_add3_u32 v0, 0, v241, v0
	v_cvt_pk_bf16_f32 v2, v2, s0
	ds_write_b16 v27, v29 offset:34816
	ds_write_b16 v0, v2 offset:35088
	v_sub_f32_e32 v2, v26, v18
	v_mul_f32_e32 v2, v19, v2
	v_fma_f32 v2, v16, v2, v24
	v_and_b32_e32 v3, 0xffff0000, v3
	v_cvt_pk_bf16_f32 v2, v2, s0
	ds_write_b16 v0, v2 offset:35360
	v_sub_f32_e32 v2, v3, v18
	v_mul_f32_e32 v2, v19, v2
	v_fmac_f32_e32 v25, v17, v2
	v_lshlrev_b32_e32 v27, 16, v4
	v_cvt_pk_bf16_f32 v2, v25, s0
	ds_write_b16 v0, v2 offset:35632
	v_sub_f32_e32 v2, v27, v18
	v_mul_f32_e32 v2, v19, v2
	v_fma_f32 v2, v6, v2, v10
	v_and_b32_e32 v4, 0xffff0000, v4
	v_cvt_pk_bf16_f32 v2, v2, s0
	ds_write_b16 v0, v2 offset:35904
	v_sub_f32_e32 v2, v4, v18
	v_mul_f32_e32 v2, v19, v2
	v_fma_f32 v2, v7, v2, v11
	v_lshlrev_b32_e32 v28, 16, v5
	v_cvt_pk_bf16_f32 v2, v2, s0
	ds_write_b16 v0, v2 offset:36176
	v_sub_f32_e32 v2, v28, v18
	v_mul_f32_e32 v2, v19, v2
	v_fma_f32 v2, v8, v2, v12
	v_and_b32_e32 v5, 0xffff0000, v5
	v_cvt_pk_bf16_f32 v2, v2, s0
	v_sub_f32_e32 v21, v21, v18
	ds_write_b16 v0, v2 offset:36448
	v_sub_f32_e32 v2, v5, v18
	v_mul_f32_e32 v21, v19, v21
	v_mul_f32_e32 v2, v19, v2
	v_fma_f32 v14, v14, v21, v22
	v_fmac_f32_e32 v13, v9, v2
	v_cvt_pk_bf16_f32 v14, v14, s0
	v_cvt_pk_bf16_f32 v2, v13, s0
	ds_write_b16 v0, v14 offset:34816
	ds_write_b16 v0, v2 offset:36720
	v_and_b32_e32 v0, 31, v34
	v_readlane_b32 s34, v253, 18
	v_lshlrev_b32_e32 v3, 4, v46
	s_waitcnt lgkmcnt(0)
	v_or_b32_e32 v2, s34, v0
	v_readlane_b32 s34, v253, 30
	v_lshrrev_b32_e32 v242, 3, v2
	v_mul_u32_u24_e32 v2, 0x110, v2
	s_barrier
; #define LAS __attribute__((address_space(3)))
; template <bool STORE> __device__ __forceinline__ void sgu_unit(LAS unsigned char* lds, const bf16_t* GEL, const float* STAT, bf16_t* GU, const float* sw, const float* sb, const float* lng, const float* lnb, int unit, const int wave_s) {
;     ...
; #pragma unroll
;     for (int ks = 0; ks < 8; ++ks) {
;         const bf16x8 af = *(const LAS bf16x8*)(lds + SG_GL + (32 * cb + q) * 272 + (16 * ks + 8 * hi) * 2);
;         const bf16x8 b0 = *(const LAS bf16x8*)(lds + SG_WL + (64 * th + q) * 272 + (16 * ks + 8 * hi) * 2);
;         const bf16x8 b1 = *(const LAS bf16x8*)(lds + SG_WL + (64 * th + 32 + q) * 272 + (16 * ks + 8 * hi) * 2);
;         d0 = __builtin_amdgcn_mfma_f32_32x32x16_bf16(af, b0, d0, 0, 0, 0);
;         d1 = __builtin_amdgcn_mfma_f32_32x32x16_bf16(af, b1, d1, 0, 0, 0);
;     }
; #pragma unroll
;     for (int tb = 0; tb < 2; ++tb) { const int t = 64 * th + 32 * tb + q; const float bias = sb[g * 128 + t];
;         bf16_t* rowp = GU + (size_t)(tok0 + t) * DM + c0 + 32 * cb + 4 * hi;
; #pragma unroll
;         for (int i = 0; i < 4; ++i) { const u32x2 u = *(const u32x2*)(rowp + 8 * i);
	v_or_b32_e32 v47, s34, v0
	v_mul_lo_u32 v0, v47, s45
	v_add3_u32 v0, 0, v0, v3
	v_add3_u32 v48, 0, v2, v3
	v_and_b32_e32 v243, 1, v242
	v_xor_b32_e32 v243, v243, v46
	v_lshrrev_b32_e32 v242, 1, v242
	v_lshl_add_u32 v244, v243, 4, v2
	ds_read_b128 v[2:5], v0 offset:8704
	v_xor_b32_e32 v245, 0, v242
	v_lshl_add_u32 v245, v245, 5, v244
	ds_read_b128 v[6:9], v245 offset:34816
	v_xor_b32_e32 v245, 1, v242
	v_lshl_add_u32 v245, v245, 5, v244
	ds_read_b128 v[34:37], v245 offset:34816
	ds_read_b128 v[10:13], v0
	ds_read_b128 v[38:41], v0 offset:32
	s_waitcnt lgkmcnt(1)
	v_mfma_f32_32x32x16_bf16 v[18:33], v[6:9], v[10:13], 0
	ds_read_b128 v[42:45], v0 offset:8736
	s_lshl_b32 s34, s44, 1
	s_add_u32 s34, s40, s34
	s_addc_u32 s35, s41, 0
	v_mfma_f32_32x32x16_bf16 v[2:17], v[6:9], v[2:5], 0
	s_waitcnt lgkmcnt(1)
	v_mfma_f32_32x32x16_bf16 v[18:33], v[34:37], v[38:41], v[18:33]
	s_waitcnt lgkmcnt(0)
	v_mfma_f32_32x32x16_bf16 v[2:17], v[34:37], v[42:45], v[2:17]
	v_xor_b32_e32 v245, 2, v242
	v_lshl_add_u32 v245, v245, 5, v244
	ds_read_b128 v[34:37], v245 offset:34816
	ds_read_b128 v[38:41], v0 offset:64
	ds_read_b128 v[42:45], v0 offset:8768
	s_waitcnt lgkmcnt(1)
	v_mfma_f32_32x32x16_bf16 v[18:33], v[34:37], v[38:41], v[18:33]
	s_waitcnt lgkmcnt(0)
	v_mfma_f32_32x32x16_bf16 v[2:17], v[34:37], v[42:45], v[2:17]
	v_xor_b32_e32 v245, 3, v242
	v_lshl_add_u32 v245, v245, 5, v244
	ds_read_b128 v[34:37], v245 offset:34816
	ds_read_b128 v[38:41], v0 offset:96
	ds_read_b128 v[42:45], v0 offset:8800
	s_waitcnt lgkmcnt(1)
	v_mfma_f32_32x32x16_bf16 v[18:33], v[34:37], v[38:41], v[18:33]
	s_waitcnt lgkmcnt(0)
	v_mfma_f32_32x32x16_bf16 v[2:17], v[34:37], v[42:45], v[2:17]
	v_xor_b32_e32 v245, 4, v242
	v_lshl_add_u32 v245, v245, 5, v244
	ds_read_b128 v[34:37], v245 offset:34816
	ds_read_b128 v[38:41], v0 offset:128
	ds_read_b128 v[42:45], v0 offset:8832
	s_waitcnt lgkmcnt(1)
	v_mfma_f32_32x32x16_bf16 v[18:33], v[34:37], v[38:41], v[18:33]
	s_waitcnt lgkmcnt(0)
	v_mfma_f32_32x32x16_bf16 v[2:17], v[34:37], v[42:45], v[2:17]
	v_xor_b32_e32 v245, 5, v242
	v_lshl_add_u32 v245, v245, 5, v244
	ds_read_b128 v[34:37], v245 offset:34816
	ds_read_b128 v[38:41], v0 offset:160
	ds_read_b128 v[42:45], v0 offset:8864
	s_waitcnt lgkmcnt(1)
	v_mfma_f32_32x32x16_bf16 v[18:33], v[34:37], v[38:41], v[18:33]
	s_waitcnt lgkmcnt(0)
	v_mfma_f32_32x32x16_bf16 v[2:17], v[34:37], v[42:45], v[2:17]
	v_xor_b32_e32 v245, 6, v242
	v_lshl_add_u32 v245, v245, 5, v244
	ds_read_b128 v[34:37], v245 offset:34816
	ds_read_b128 v[38:41], v0 offset:192
	ds_read_b128 v[42:45], v0 offset:8896
	s_waitcnt lgkmcnt(1)
	v_mfma_f32_32x32x16_bf16 v[18:33], v[34:37], v[38:41], v[18:33]
	s_waitcnt lgkmcnt(0)
	v_mfma_f32_32x32x16_bf16 v[2:17], v[34:37], v[42:45], v[2:17]
	v_xor_b32_e32 v245, 7, v242
	v_lshl_add_u32 v245, v245, 5, v244
	ds_read_b128 v[34:37], v245 offset:34816
	ds_read_b128 v[38:41], v0 offset:224
	ds_read_b128 v[42:45], v0 offset:8928
	v_lshlrev_b32_e32 v0, 3, v46
	s_waitcnt lgkmcnt(1)
	v_mfma_f32_32x32x16_bf16 v[18:33], v[34:37], v[38:41], v[18:33]
	v_add_u32_e32 v38, s43, v47
	v_ashrrev_i32_e32 v39, 31, v38
	v_lshlrev_b64 v[40:41], 11, v[38:39]
	s_waitcnt lgkmcnt(0)
	v_mfma_f32_32x32x16_bf16 v[2:17], v[34:37], v[42:45], v[2:17]
	v_lshl_add_u64 v[34:35], s[34:35], 0, v[0:1]
	v_add_u32_e32 v0, s44, v47
	v_lshl_add_u64 v[36:37], v[0:1], 2, s[12:13]
	v_lshl_add_u64 v[40:41], v[34:35], 0, v[40:41]
	v_add_u32_e32 v170, 32, v38
	v_ashrrev_i32_e32 v171, 31, v170
	v_lshlrev_b64 v[170:171], 11, v[170:171]
	v_lshl_add_u64 v[170:171], v[34:35], 0, v[170:171]
	global_load_dword v168, v[36:37], off
	global_load_dwordx2 v[150:151], v[40:41], off
	global_load_dwordx2 v[152:153], v[40:41], off offset:16
	global_load_dwordx2 v[154:155], v[40:41], off offset:32
	global_load_dwordx2 v[156:157], v[40:41], off offset:48
	global_load_dword v169, v[36:37], off offset:128
	global_load_dwordx2 v[158:159], v[170:171], off
	global_load_dwordx2 v[160:161], v[170:171], off offset:16
	global_load_dwordx2 v[162:163], v[170:171], off offset:32
	global_load_dwordx2 v[164:165], v[170:171], off offset:48
	s_waitcnt vmcnt(8)
; __device__ __forceinline__ unsigned cvt_pk_bf16(float lo, float hi) { const f32x2 v = {lo, hi}; const bf16x2_t b = __builtin_convertvector(v, bf16x2_t); return __builtin_bit_cast(unsigned, b); }
; __device__ __forceinline__ float bf_lo(unsigned u) { return __uint_as_float(u << 16); }
; __device__ __forceinline__ float bf_hi(unsigned u) { return __uint_as_float(u & 0xffff0000u); }
; template <bool STORE> __device__ __forceinline__ void sgu_unit(LAS unsigned char* lds, const bf16_t* GEL, const float* STAT, bf16_t* GU, const float* sw, const float* sb, const float* lng, const float* lnb, int unit, const int wave_s) {
;     ...
;     for (int tb = 0; tb < 2; ++tb) { const int t = 64 * th + 32 * tb + q; const float bias = sb[g * 128 + t];
;         bf16_t* rowp = GU + (size_t)(tok0 + t) * DM + c0 + 32 * cb + 4 * hi;
; #pragma unroll
;         for (int i = 0; i < 4; ++i) { const u32x2 u = *(const u32x2*)(rowp + 8 * i);
;             const float m0 = (tb ? d1[4 * i] : d0[4 * i]) + bias, m1 = (tb ? d1[4 * i + 1] : d0[4 * i + 1]) + bias, m2 = (tb ? d1[4 * i + 2] : d0[4 * i + 2]) + bias, m3 = (tb ? d1[4 * i + 3] : d0[4 * i + 3]) + bias;
;             u32x2 w; w.x = cvt_pk_bf16(bf_lo(u.x) * m0, bf_hi(u.x) * m1); w.y = cvt_pk_bf16(bf_lo(u.y) * m2, bf_hi(u.y) * m3);
;             if (STORE) *(u32x2*)(rowp + 8 * i) = w; } }
	v_add_f32_e32 v18, v18, v168
	v_add_f32_e32 v19, v19, v168
	v_add_f32_e32 v20, v20, v168
	v_add_f32_e32 v21, v21, v168
	v_lshlrev_b32_e32 v172, 16, v150
	v_and_b32_e32 v173, 0xffff0000, v150
	v_mul_f32_e32 v18, v18, v172
	v_mul_f32_e32 v19, v19, v173
	v_lshlrev_b32_e32 v172, 16, v151
	v_and_b32_e32 v173, 0xffff0000, v151
	v_mul_f32_e32 v20, v20, v172
	v_mul_f32_e32 v21, v21, v173
	v_cvt_pk_bf16_f32 v18, v18, v19
	v_cvt_pk_bf16_f32 v19, v20, v21
	global_store_dwordx2 v[40:41], v[18:19], off
	s_waitcnt vmcnt(8)
	v_add_f32_e32 v22, v22, v168
	v_add_f32_e32 v23, v23, v168
	v_add_f32_e32 v24, v24, v168
	v_add_f32_e32 v25, v25, v168
	v_lshlrev_b32_e32 v172, 16, v152
	v_and_b32_e32 v173, 0xffff0000, v152
	v_mul_f32_e32 v22, v22, v172
	v_mul_f32_e32 v23, v23, v173
	v_lshlrev_b32_e32 v172, 16, v153
	v_and_b32_e32 v173, 0xffff0000, v153
	v_mul_f32_e32 v24, v24, v172
	v_mul_f32_e32 v25, v25, v173
	v_cvt_pk_bf16_f32 v22, v22, v23
	v_cvt_pk_bf16_f32 v23, v24, v25
	global_store_dwordx2 v[40:41], v[22:23], off offset:16
	s_waitcnt vmcnt(8)
	v_add_f32_e32 v26, v26, v168
	v_add_f32_e32 v27, v27, v168
	v_add_f32_e32 v28, v28, v168
	v_add_f32_e32 v29, v29, v168
	v_lshlrev_b32_e32 v172, 16, v154
	v_and_b32_e32 v173, 0xffff0000, v154
	v_mul_f32_e32 v26, v26, v172
	v_mul_f32_e32 v27, v27, v173
	v_lshlrev_b32_e32 v172, 16, v155
	v_and_b32_e32 v173, 0xffff0000, v155
	v_mul_f32_e32 v28, v28, v172
	v_mul_f32_e32 v29, v29, v173
	v_cvt_pk_bf16_f32 v26, v26, v27
	v_cvt_pk_bf16_f32 v27, v28, v29
	global_store_dwordx2 v[40:41], v[26:27], off offset:32
	s_waitcnt vmcnt(8)
	v_add_f32_e32 v30, v30, v168
	v_add_f32_e32 v31, v31, v168
	v_add_f32_e32 v32, v32, v168
	v_add_f32_e32 v33, v33, v168
	v_lshlrev_b32_e32 v172, 16, v156
	v_and_b32_e32 v173, 0xffff0000, v156
	v_mul_f32_e32 v30, v30, v172
	v_mul_f32_e32 v31, v31, v173
	v_lshlrev_b32_e32 v172, 16, v157
	v_and_b32_e32 v173, 0xffff0000, v157
	v_mul_f32_e32 v32, v32, v172
	v_mul_f32_e32 v33, v33, v173
	v_cvt_pk_bf16_f32 v30, v30, v31
	v_cvt_pk_bf16_f32 v31, v32, v33
	global_store_dwordx2 v[40:41], v[30:31], off offset:48
	s_waitcnt vmcnt(7)
	v_add_f32_e32 v2, v2, v169
	v_add_f32_e32 v3, v3, v169
	v_add_f32_e32 v4, v4, v169
	v_add_f32_e32 v5, v5, v169
	v_lshlrev_b32_e32 v172, 16, v158
	v_and_b32_e32 v173, 0xffff0000, v158
	v_mul_f32_e32 v2, v2, v172
	v_mul_f32_e32 v3, v3, v173
	v_lshlrev_b32_e32 v172, 16, v159
	v_and_b32_e32 v173, 0xffff0000, v159
	v_mul_f32_e32 v4, v4, v172
	v_mul_f32_e32 v5, v5, v173
	v_cvt_pk_bf16_f32 v2, v2, v3
	v_cvt_pk_bf16_f32 v3, v4, v5
	global_store_dwordx2 v[170:171], v[2:3], off
	s_waitcnt vmcnt(7)
	v_add_f32_e32 v6, v6, v169
	v_add_f32_e32 v7, v7, v169
	v_add_f32_e32 v8, v8, v169
	v_add_f32_e32 v9, v9, v169
	v_lshlrev_b32_e32 v172, 16, v160
	v_and_b32_e32 v173, 0xffff0000, v160
	v_mul_f32_e32 v6, v6, v172
	v_mul_f32_e32 v7, v7, v173
	v_lshlrev_b32_e32 v172, 16, v161
	v_and_b32_e32 v173, 0xffff0000, v161
	v_mul_f32_e32 v8, v8, v172
	v_mul_f32_e32 v9, v9, v173
	v_cvt_pk_bf16_f32 v6, v6, v7
	v_cvt_pk_bf16_f32 v7, v8, v9
	global_store_dwordx2 v[170:171], v[6:7], off offset:16
	s_waitcnt vmcnt(7)
	v_add_f32_e32 v10, v10, v169
	v_add_f32_e32 v11, v11, v169
	v_add_f32_e32 v12, v12, v169
	v_add_f32_e32 v13, v13, v169
	v_lshlrev_b32_e32 v172, 16, v162
	v_and_b32_e32 v173, 0xffff0000, v162
	v_mul_f32_e32 v10, v10, v172
	v_mul_f32_e32 v11, v11, v173
	v_lshlrev_b32_e32 v172, 16, v163
	v_and_b32_e32 v173, 0xffff0000, v163
	v_mul_f32_e32 v12, v12, v172
	v_mul_f32_e32 v13, v13, v173
	v_cvt_pk_bf16_f32 v10, v10, v11
	v_cvt_pk_bf16_f32 v11, v12, v13
	global_store_dwordx2 v[170:171], v[10:11], off offset:32
	s_waitcnt vmcnt(7)
	v_add_f32_e32 v14, v14, v169
	v_add_f32_e32 v15, v15, v169
	v_add_f32_e32 v16, v16, v169
	v_add_f32_e32 v17, v17, v169
	v_lshlrev_b32_e32 v172, 16, v164
	v_and_b32_e32 v173, 0xffff0000, v164
	v_mul_f32_e32 v14, v14, v172
	v_mul_f32_e32 v15, v15, v173
	v_lshlrev_b32_e32 v172, 16, v165
	v_and_b32_e32 v173, 0xffff0000, v165
	v_mul_f32_e32 v16, v16, v172
	v_mul_f32_e32 v17, v17, v173
	v_cvt_pk_bf16_f32 v14, v14, v15
	v_cvt_pk_bf16_f32 v15, v16, v17
	global_store_dwordx2 v[170:171], v[14:15], off offset:48
	s_barrier
